# differential attention diagonal tiles: packed fp32 add/fma split into single-lane ops (7.5 packed vs scalar), on top of the LayerNorm pack rewrite
# speedup vs baseline: 1.0254x; 1.0089x over previous
.LBB0_305:
	v_readlane_b32 vcc_lo, v252, 58
	v_readlane_b32 vcc_hi, v252, 59
	v_add_f32_e32 v77, -1.0, v76
	s_nop 0
	v_cndmask_b32_e64 v32, 0, 1, vcc
	v_cmp_ne_u32_e64 s[12:13], 1, v32
	s_andn2_b64 vcc, exec, vcc
	s_cbranch_vccnz .LBB0_307
	s_mov_b32 s62, -2.0
	s_mov_b32 s52, 0xc1800000
	s_mov_b32 s63, 0xc0400000
	s_mov_b32 s53, 0xc1880000
	v_add_f32_e64 v32, v76, s62
	v_add_f32_e64 v33, v76, s63
	s_mov_b32 s62, 0xc1900000
	v_add_f32_e64 v38, v76, s52
	v_add_f32_e64 v39, v76, s53
	s_mov_b32 s52, 0xc1c00000
	s_mov_b32 s63, 0xc1980000
	s_mov_b32 s53, 0xc1c80000
	v_add_f32_e64 v34, v76, s68
	v_add_f32_e64 v35, v76, s69
	v_add_f32_e64 v36, v76, s70
	v_add_f32_e64 v37, v76, s71
	v_add_f32_e64 v40, v76, s62
	v_add_f32_e64 v41, v76, s63
	v_add_f32_e64 v42, v76, s52
	v_add_f32_e64 v43, v76, s53
	v_add_f32_e64 v44, v76, s54
	v_add_f32_e64 v45, v76, s55
	v_and_b32_e32 v45, 0x7fffffff, v45
	v_and_b32_e32 v44, 0x7fffffff, v44
	v_and_b32_e32 v43, 0x7fffffff, v43
	v_and_b32_e32 v42, 0x7fffffff, v42
	v_and_b32_e32 v41, 0x7fffffff, v41
	v_and_b32_e32 v40, 0x7fffffff, v40
	v_and_b32_e32 v39, 0x7fffffff, v39
	v_and_b32_e32 v38, 0x7fffffff, v38
	v_and_b32_e32 v37, 0x7fffffff, v37
	v_and_b32_e32 v36, 0x7fffffff, v36
	v_and_b32_e32 v35, 0x7fffffff, v35
	v_and_b32_e32 v34, 0x7fffffff, v34
	v_and_b32_e32 v33, 0x7fffffff, v33
	v_and_b32_e32 v32, 0x7fffffff, v32
	v_and_b32_e32 v46, 0x7fffffff, v76
	v_and_b32_e32 v47, 0x7fffffff, v77
	v_fma_f32 v2, -v156, v32, v2
	v_fma_f32 v3, -v156, v33, v3
	v_fma_f32 v4, -v156, v34, v4
	v_fma_f32 v5, -v156, v35, v5
	v_fma_f32 v6, -v156, v36, v6
	v_fma_f32 v7, -v156, v37, v7
	v_fma_f32 v8, -v156, v38, v8
	v_fma_f32 v9, -v156, v39, v9
	v_fma_f32 v10, -v156, v40, v10
	v_fma_f32 v11, -v156, v41, v11
	v_fma_f32 v12, -v156, v42, v12
	v_fma_f32 v13, -v156, v43, v13
	v_fma_f32 v14, -v156, v44, v14
	v_fma_f32 v15, -v156, v45, v15
	v_fma_f32 v0, -v156, v46, v0
	v_fma_f32 v1, -v156, v47, v1
	v_sub_f32_e32 v15, v15, v155
	v_sub_f32_e32 v14, v14, v155
	v_sub_f32_e32 v13, v13, v155
	v_sub_f32_e32 v12, v12, v155
	v_sub_f32_e32 v11, v11, v155
	v_sub_f32_e32 v10, v10, v155
	v_sub_f32_e32 v9, v9, v155
	v_sub_f32_e32 v8, v8, v155
	v_sub_f32_e32 v7, v7, v155
	v_sub_f32_e32 v6, v6, v155
	v_sub_f32_e32 v5, v5, v155
	v_sub_f32_e32 v4, v4, v155
	v_sub_f32_e32 v3, v3, v155
	v_sub_f32_e32 v2, v2, v155
	v_sub_f32_e32 v1, v1, v155
	v_sub_f32_e32 v0, v0, v155
.LBB0_307:
	v_add_u32_e32 v78, s6, v162
	v_mfma_f32_32x32x16_bf16 v[52:67], v[28:31], v[96:99], v[52:67]
	ds_read_b64_tr_b16 v[44:45], v78 offset:16384
	ds_read_b64_tr_b16 v[46:47], v78 offset:16896
	ds_read_b64_tr_b16 v[40:41], v78 offset:17408
	ds_read_b64_tr_b16 v[42:43], v78 offset:17920
	v_mfma_f32_32x32x16_bf16 v[52:67], v[24:27], v[100:103], v[52:67]
	ds_read_b64_tr_b16 v[28:29], v78 offset:20480
	ds_read_b64_tr_b16 v[30:31], v78 offset:20992
	ds_read_b64_tr_b16 v[36:37], v78 offset:21504
	ds_read_b64_tr_b16 v[38:39], v78 offset:22016
	v_mfma_f32_32x32x16_bf16 v[52:67], v[20:23], v[104:107], v[52:67]
	ds_read_b64_tr_b16 v[32:33], v78 offset:24576
	ds_read_b64_tr_b16 v[34:35], v78 offset:25088
	ds_read_b64_tr_b16 v[72:73], v78 offset:25600
	ds_read_b64_tr_b16 v[74:75], v78 offset:26112
	s_waitcnt lgkmcnt(12)
	v_mfma_f32_32x32x16_bf16 v[52:67], v[16:19], v[108:111], v[52:67]
	ds_read_b64_tr_b16 v[48:49], v78 offset:28672
	ds_read_b64_tr_b16 v[50:51], v78 offset:29184
	ds_read_b64_tr_b16 v[68:69], v78 offset:29696
	ds_read_b64_tr_b16 v[70:71], v78 offset:30208
	s_and_b64 vcc, exec, s[12:13]
	s_cbranch_vccnz .LBB0_309
	s_mov_b32 s6, -2.0
	s_mov_b32 s7, 0xc0400000
	v_add_f32_e64 v16, v76, s6
	v_add_f32_e64 v17, v76, s7
	s_mov_b32 s6, 0xc1800000
	s_mov_b32 s7, 0xc1880000
	v_add_f32_e64 v22, v76, s6
	v_add_f32_e64 v23, v76, s7
	s_mov_b32 s6, 0xc1c00000
	s_mov_b32 s7, 0xc1c80000
	v_add_f32_e64 v18, v76, s68
	v_add_f32_e64 v19, v76, s69
	v_add_f32_e64 v20, v76, s70
	v_add_f32_e64 v21, v76, s71
	v_add_f32_e64 v24, v76, s62
	v_add_f32_e64 v25, v76, s63
	v_add_f32_e64 v26, v76, s6
	v_add_f32_e64 v27, v76, s7
	v_add_f32_e64 v80, v76, s54
	v_add_f32_e64 v81, v76, s55
	s_mov_b32 s6, 0xc2000000
	v_add_f32_e64 v76, v76, s6
	v_add_f32_e64 v77, v77, s6
	v_add_f32_e64 v16, v16, s6
	v_add_f32_e64 v17, v17, s6
	v_add_f32_e64 v18, v18, s6
	v_add_f32_e64 v19, v19, s6
	v_add_f32_e64 v20, v20, s6
	v_add_f32_e64 v21, v21, s6
	v_add_f32_e64 v22, v22, s6
	v_add_f32_e64 v23, v23, s6
	v_add_f32_e64 v24, v24, s6
	v_add_f32_e64 v25, v25, s6
	v_add_f32_e64 v26, v26, s6
	v_add_f32_e64 v27, v27, s6
	v_add_f32_e64 v80, v80, s6
	v_add_f32_e64 v81, v81, s6
	v_and_b32_e32 v27, 0x7fffffff, v27
	v_and_b32_e32 v81, 0x7fffffff, v81
	v_and_b32_e32 v80, 0x7fffffff, v80
	v_and_b32_e32 v26, 0x7fffffff, v26
	v_and_b32_e32 v25, 0x7fffffff, v25
	v_and_b32_e32 v24, 0x7fffffff, v24
	v_and_b32_e32 v23, 0x7fffffff, v23
	v_and_b32_e32 v22, 0x7fffffff, v22
	v_and_b32_e32 v21, 0x7fffffff, v21
	v_and_b32_e32 v20, 0x7fffffff, v20
	v_and_b32_e32 v19, 0x7fffffff, v19
	v_and_b32_e32 v18, 0x7fffffff, v18
	v_and_b32_e32 v17, 0x7fffffff, v17
	v_and_b32_e32 v16, 0x7fffffff, v16
	v_and_b32_e32 v77, 0x7fffffff, v77
	v_and_b32_e32 v76, 0x7fffffff, v76
	v_fma_f32 v52, -v156, v76, v52
	v_fma_f32 v53, -v156, v77, v53
	v_fma_f32 v16, -v156, v16, v54
	v_fma_f32 v17, -v156, v17, v55
	v_fma_f32 v18, -v156, v18, v56
	v_fma_f32 v19, -v156, v19, v57
	v_fma_f32 v20, -v156, v20, v58
	v_fma_f32 v21, -v156, v21, v59
	v_fma_f32 v22, -v156, v22, v60
	v_fma_f32 v23, -v156, v23, v61
	v_fma_f32 v24, -v156, v24, v62
	v_fma_f32 v25, -v156, v25, v63
	v_fma_f32 v26, -v156, v26, v64
	v_fma_f32 v27, -v156, v27, v65
	v_fma_f32 v54, -v156, v80, v66
	v_fma_f32 v55, -v156, v81, v67
	v_sub_f32_e32 v67, v55, v155
	v_sub_f32_e32 v66, v54, v155
	v_sub_f32_e32 v65, v27, v155
	v_sub_f32_e32 v64, v26, v155
	v_sub_f32_e32 v63, v25, v155
	v_sub_f32_e32 v62, v24, v155
	v_sub_f32_e32 v61, v23, v155
	v_sub_f32_e32 v60, v22, v155
	v_sub_f32_e32 v59, v21, v155
	v_sub_f32_e32 v58, v20, v155
	v_sub_f32_e32 v57, v19, v155
	v_sub_f32_e32 v56, v18, v155
	v_sub_f32_e32 v55, v17, v155
	v_sub_f32_e32 v54, v16, v155
	v_sub_f32_e32 v53, v53, v155
	v_sub_f32_e32 v52, v52, v155

.LBB0_313:
	s_and_b64 vcc, exec, s[10:11]
	v_add_f32_e32 v161, -1.0, v160
	s_cbranch_vccnz .LBB0_315
	s_mov_b32 s6, -2.0
	s_mov_b32 s7, 0xc0400000
	v_add_f32_e64 v128, v160, s6
	v_add_f32_e64 v129, v160, s7
	s_mov_b32 s6, 0xc1800000
	s_mov_b32 s7, 0xc1880000
	v_add_f32_e64 v134, v160, s6
	v_add_f32_e64 v135, v160, s7
	s_mov_b32 s6, 0xc1c00000
	s_mov_b32 s7, 0xc1c80000
	v_add_f32_e64 v130, v160, s68
	v_add_f32_e64 v131, v160, s69
	v_add_f32_e64 v132, v160, s70
	v_add_f32_e64 v133, v160, s71
	v_add_f32_e64 v136, v160, s62
	v_add_f32_e64 v137, v160, s63
	v_add_f32_e64 v138, v160, s6
	v_add_f32_e64 v139, v160, s7
	v_add_f32_e64 v140, v160, s54
	v_add_f32_e64 v141, v160, s55
	v_and_b32_e32 v141, 0x7fffffff, v141
	v_and_b32_e32 v140, 0x7fffffff, v140
	v_and_b32_e32 v139, 0x7fffffff, v139
	v_and_b32_e32 v138, 0x7fffffff, v138
	v_and_b32_e32 v137, 0x7fffffff, v137
	v_and_b32_e32 v136, 0x7fffffff, v136
	v_and_b32_e32 v135, 0x7fffffff, v135
	v_and_b32_e32 v134, 0x7fffffff, v134
	v_and_b32_e32 v133, 0x7fffffff, v133
	v_and_b32_e32 v132, 0x7fffffff, v132
	v_and_b32_e32 v131, 0x7fffffff, v131
	v_and_b32_e32 v130, 0x7fffffff, v130
	v_and_b32_e32 v129, 0x7fffffff, v129
	v_and_b32_e32 v128, 0x7fffffff, v128
	v_and_b32_e32 v142, 0x7fffffff, v160
	v_and_b32_e32 v143, 0x7fffffff, v161
	v_fma_f32 v82, -v156, v128, v82
	v_fma_f32 v83, -v156, v129, v83
	v_fma_f32 v84, -v156, v130, v84
	v_fma_f32 v85, -v156, v131, v85
	v_fma_f32 v86, -v156, v132, v86
	v_fma_f32 v87, -v156, v133, v87
	v_fma_f32 v88, -v156, v134, v88
	v_fma_f32 v89, -v156, v135, v89
	v_fma_f32 v90, -v156, v136, v90
	v_fma_f32 v91, -v156, v137, v91
	v_fma_f32 v92, -v156, v138, v92
	v_fma_f32 v93, -v156, v139, v93
	v_fma_f32 v94, -v156, v140, v94
	v_fma_f32 v95, -v156, v141, v95
	v_fma_f32 v80, -v156, v142, v80
	v_fma_f32 v81, -v156, v143, v81
	v_sub_f32_e32 v95, v95, v155
	v_sub_f32_e32 v94, v94, v155
	v_sub_f32_e32 v93, v93, v155
	v_sub_f32_e32 v92, v92, v155
	v_sub_f32_e32 v91, v91, v155
	v_sub_f32_e32 v90, v90, v155
	v_sub_f32_e32 v89, v89, v155
	v_sub_f32_e32 v88, v88, v155
	v_sub_f32_e32 v87, v87, v155
	v_sub_f32_e32 v86, v86, v155
	v_sub_f32_e32 v85, v85, v155
	v_sub_f32_e32 v84, v84, v155
	v_sub_f32_e32 v83, v83, v155
	v_sub_f32_e32 v82, v82, v155
	v_sub_f32_e32 v81, v81, v155
	v_sub_f32_e32 v80, v80, v155
.LBB0_315:
	v_add_u32_e32 v202, s3, v162
	v_mfma_f32_32x32x16_bf16 v[64:79], v[120:123], v[96:99], v[64:79]
	ds_read_b64_tr_b16 v[144:145], v202 offset:16384
	ds_read_b64_tr_b16 v[146:147], v202 offset:16896
	ds_read_b64_tr_b16 v[140:141], v202 offset:17408
	ds_read_b64_tr_b16 v[142:143], v202 offset:17920
	v_mfma_f32_32x32x16_bf16 v[64:79], v[116:119], v[100:103], v[64:79]
	ds_read_b64_tr_b16 v[136:137], v202 offset:20480
	ds_read_b64_tr_b16 v[138:139], v202 offset:20992
	ds_read_b64_tr_b16 v[132:133], v202 offset:21504
	ds_read_b64_tr_b16 v[134:135], v202 offset:22016
	v_mfma_f32_32x32x16_bf16 v[64:79], v[112:115], v[104:107], v[64:79]
	ds_read_b64_tr_b16 v[128:129], v202 offset:24576
	ds_read_b64_tr_b16 v[130:131], v202 offset:25088
	ds_read_b64_tr_b16 v[120:121], v202 offset:25600
	ds_read_b64_tr_b16 v[122:123], v202 offset:26112
	s_waitcnt lgkmcnt(12)
	v_mfma_f32_32x32x16_bf16 v[64:79], v[124:127], v[108:111], v[64:79]
	ds_read_b64_tr_b16 v[116:117], v202 offset:28672
	ds_read_b64_tr_b16 v[118:119], v202 offset:29184
	ds_read_b64_tr_b16 v[112:113], v202 offset:29696
	ds_read_b64_tr_b16 v[114:115], v202 offset:30208
	s_and_b64 vcc, exec, s[10:11]
	s_cbranch_vccnz .LBB0_317
	s_mov_b32 s6, -2.0
	s_mov_b32 s7, 0xc0400000
	v_add_f32_e64 v124, v160, s6
	v_add_f32_e64 v125, v160, s7
	s_mov_b32 s6, 0xc1800000
	s_mov_b32 s7, 0xc1880000
	v_add_f32_e64 v206, v160, s6
	v_add_f32_e64 v207, v160, s7
	s_mov_b32 s6, 0xc1c00000
	s_mov_b32 s7, 0xc1c80000
	v_add_f32_e64 v126, v160, s68
	v_add_f32_e64 v127, v160, s69
	v_add_f32_e64 v204, v160, s70
	v_add_f32_e64 v205, v160, s71
	v_add_f32_e64 v208, v160, s62
	v_add_f32_e64 v209, v160, s63
	v_add_f32_e64 v210, v160, s6
	v_add_f32_e64 v211, v160, s7
	v_add_f32_e64 v212, v160, s54
	v_add_f32_e64 v213, v160, s55
	s_mov_b32 s6, 0xc2000000
	v_add_f32_e64 v160, v160, s6
	v_add_f32_e64 v161, v161, s6
	v_add_f32_e64 v124, v124, s6
	v_add_f32_e64 v125, v125, s6
	v_add_f32_e64 v126, v126, s6
	v_add_f32_e64 v127, v127, s6
	v_add_f32_e64 v204, v204, s6
	v_add_f32_e64 v205, v205, s6
	v_add_f32_e64 v206, v206, s6
	v_add_f32_e64 v207, v207, s6
	v_add_f32_e64 v208, v208, s6
	v_add_f32_e64 v209, v209, s6
	v_add_f32_e64 v210, v210, s6
	v_add_f32_e64 v211, v211, s6
	v_add_f32_e64 v212, v212, s6
	v_add_f32_e64 v213, v213, s6
	v_and_b32_e32 v211, 0x7fffffff, v211
	v_and_b32_e32 v213, 0x7fffffff, v213
	v_and_b32_e32 v212, 0x7fffffff, v212
	v_and_b32_e32 v210, 0x7fffffff, v210
	v_and_b32_e32 v209, 0x7fffffff, v209
	v_and_b32_e32 v208, 0x7fffffff, v208
	v_and_b32_e32 v207, 0x7fffffff, v207
	v_and_b32_e32 v206, 0x7fffffff, v206
	v_and_b32_e32 v205, 0x7fffffff, v205
	v_and_b32_e32 v204, 0x7fffffff, v204
	v_and_b32_e32 v127, 0x7fffffff, v127
	v_and_b32_e32 v126, 0x7fffffff, v126
	v_and_b32_e32 v125, 0x7fffffff, v125
	v_and_b32_e32 v124, 0x7fffffff, v124
	v_and_b32_e32 v161, 0x7fffffff, v161
	v_and_b32_e32 v160, 0x7fffffff, v160
	v_fma_f32 v64, -v156, v160, v64
	v_fma_f32 v65, -v156, v161, v65
	v_fma_f32 v66, -v156, v124, v66
	v_fma_f32 v67, -v156, v125, v67
	v_fma_f32 v68, -v156, v126, v68
	v_fma_f32 v69, -v156, v127, v69
	v_fma_f32 v70, -v156, v204, v70
	v_fma_f32 v71, -v156, v205, v71
	v_fma_f32 v72, -v156, v206, v72
	v_fma_f32 v73, -v156, v207, v73
	v_fma_f32 v74, -v156, v208, v74
	v_fma_f32 v75, -v156, v209, v75
	v_fma_f32 v76, -v156, v210, v76
	v_fma_f32 v77, -v156, v211, v77
	v_fma_f32 v78, -v156, v212, v78
	v_fma_f32 v79, -v156, v213, v79
	v_sub_f32_e32 v79, v79, v155
	v_sub_f32_e32 v78, v78, v155
	v_sub_f32_e32 v77, v77, v155
	v_sub_f32_e32 v76, v76, v155
	v_sub_f32_e32 v75, v75, v155
	v_sub_f32_e32 v74, v74, v155
	v_sub_f32_e32 v73, v73, v155
	v_sub_f32_e32 v72, v72, v155
	v_sub_f32_e32 v71, v71, v155
	v_sub_f32_e32 v70, v70, v155
	v_sub_f32_e32 v69, v69, v155
	v_sub_f32_e32 v68, v68, v155
	v_sub_f32_e32 v67, v67, v155
	v_sub_f32_e32 v66, v66, v155
	v_sub_f32_e32 v65, v65, v155
	v_sub_f32_e32 v64, v64, v155
